# as previous + nt cache policy on the G2 epilogue residual loads (both layers)
# baseline (speedup 1.0000x reference)
;     __device__ __forceinline__ void operator()(const f32x4 (&acc)[2][2][4][2], const pg8::Unit& u, int wr, int wc, int fr, int fq) const {
;     ...
;         const float* gp = gatev + (size_t)(u.pm >> 3) * 3072 + col0;
;         f32x4 gv[2][2];
; #pragma unroll
;         for (int bj = 0; bj < 2; ++bj)
; #pragma unroll
;             for (int n = 0; n < 2; ++n) gv[bj][n] = *(const f32x4*)(gp + bj * 128 + n * 16);
; #pragma unroll
;         for (int ai = 0; ai < 2; ++ai)
; #pragma unroll
;             for (int m = 0; m < 4; ++m) {
;                 const size_t off = (size_t)(row0 + ai * 128 + m * 16) * DM + col0;
; #pragma unroll
;                 for (int bj = 0; bj < 2; ++bj)
; #pragma unroll
;                     for (int n = 0; n < 2; ++n) {
;                         const f32x4 xv = *(const f32x4*)(xin + off + bj * 128 + n * 16);
;                         *(f32x4*)(out + off + bj * 128 + n * 16) = xv + gv[bj][n] * acc[ai][bj][m][n];
;                     }
;                 if (m == 3) asm volatile("" ::: "memory");
;             }
.LBB0_582:
	v_lshl_add_u32 v170, s30, 8, v158
	v_lshl_or_b32 v168, s56, 8, v160
	s_ashr_i32 s23, s30, 3
	v_ashrrev_i32_e32 v171, 31, v170
	s_mul_hi_i32 s25, s23, 0x3000
	s_mulk_i32 s23, 0x3000
	v_ashrrev_i32_e32 v169, 31, v168
	v_lshlrev_b64 v[130:131], 10, v[170:171]
	s_add_u32 s34, s49, s23
	v_lshl_add_u64 v[130:131], v[130:131], 0, v[168:169]
	s_addc_u32 s35, s50, s25
	v_lshlrev_b64 v[156:157], 2, v[130:131]
	v_lshl_add_u64 v[128:129], v[168:169], 2, s[34:35]
	global_load_dwordx4 v[140:143], v[128:129], off
	global_load_dwordx4 v[136:139], v[128:129], off offset:64
	global_load_dwordx4 v[132:135], v[128:129], off offset:512
	s_nop 0
	global_load_dwordx4 v[128:131], v[128:129], off offset:576
	s_andn2_b64 vcc, exec, s[4:5]
	s_mov_b64 s[4:5], -1
	s_mov_b64 s[36:37], s[0:1]
	global_load_dwordx4 v[164:167], v156, s[36:37] nt
	global_load_dwordx4 v[168:171], v156, s[36:37] offset:64 nt
	global_load_dwordx4 v[172:175], v156, s[36:37] offset:512 nt
	global_load_dwordx4 v[176:179], v156, s[36:37] offset:576 nt
	s_add_u32 s36, s0, 0x10000
	s_addc_u32 s37, s1, 0
	global_load_dwordx4 v[180:183], v156, s[36:37] nt
	global_load_dwordx4 v[184:187], v156, s[36:37] offset:64 nt
	global_load_dwordx4 v[188:191], v156, s[36:37] offset:512 nt
	global_load_dwordx4 v[192:195], v156, s[36:37] offset:576 nt
	s_add_u32 s36, s0, 0x20000
	s_addc_u32 s37, s1, 0
	global_load_dwordx4 v[196:199], v156, s[36:37] nt
	global_load_dwordx4 v[204:207], v156, s[36:37] offset:64 nt
	global_load_dwordx4 v[208:211], v156, s[36:37] offset:512 nt
	global_load_dwordx4 v[212:215], v156, s[36:37] offset:576 nt
	s_waitcnt vmcnt(8)
	v_pk_fma_f32 v[166:167], v[126:127], v[142:143], v[166:167]
	v_pk_fma_f32 v[164:165], v[124:125], v[140:141], v[164:165]
	v_pk_fma_f32 v[170:171], v[122:123], v[138:139], v[170:171]
	v_pk_fma_f32 v[168:169], v[120:121], v[136:137], v[168:169]
	v_pk_fma_f32 v[174:175], v[118:119], v[134:135], v[174:175]
	v_pk_fma_f32 v[172:173], v[116:117], v[132:133], v[172:173]
	v_pk_fma_f32 v[178:179], v[106:107], v[130:131], v[178:179]
	v_pk_fma_f32 v[176:177], v[104:105], v[128:129], v[176:177]
	s_mov_b64 s[38:39], s[8:9]
	global_store_dwordx4 v156, v[164:167], s[38:39]
	global_store_dwordx4 v156, v[168:171], s[38:39] offset:64
	global_store_dwordx4 v156, v[172:175], s[38:39] offset:512
	global_store_dwordx4 v156, v[176:179], s[38:39] offset:576
	s_add_u32 s36, s0, 0x30000
	s_addc_u32 s37, s1, 0
	global_load_dwordx4 v[164:167], v156, s[36:37] nt
	global_load_dwordx4 v[168:171], v156, s[36:37] offset:64 nt
	global_load_dwordx4 v[172:175], v156, s[36:37] offset:512 nt
	global_load_dwordx4 v[176:179], v156, s[36:37] offset:576 nt
	s_waitcnt vmcnt(12)
	v_pk_fma_f32 v[182:183], v[114:115], v[142:143], v[182:183]
	v_pk_fma_f32 v[180:181], v[112:113], v[140:141], v[180:181]
	v_pk_fma_f32 v[186:187], v[110:111], v[138:139], v[186:187]
	v_pk_fma_f32 v[184:185], v[108:109], v[136:137], v[184:185]
	v_pk_fma_f32 v[190:191], v[102:103], v[134:135], v[190:191]
	v_pk_fma_f32 v[188:189], v[100:101], v[132:133], v[188:189]
	v_pk_fma_f32 v[194:195], v[90:91], v[130:131], v[194:195]
	v_pk_fma_f32 v[192:193], v[88:89], v[128:129], v[192:193]
	s_add_u32 s38, s8, 0x10000
	s_addc_u32 s39, s9, 0
	global_store_dwordx4 v156, v[180:183], s[38:39]
	global_store_dwordx4 v156, v[184:187], s[38:39] offset:64
	global_store_dwordx4 v156, v[188:191], s[38:39] offset:512
	global_store_dwordx4 v156, v[192:195], s[38:39] offset:576
	s_add_u32 s36, s0, 0x80000
	s_addc_u32 s37, s1, 0
	global_load_dwordx4 v[180:183], v156, s[36:37] nt
	global_load_dwordx4 v[184:187], v156, s[36:37] offset:64 nt
	global_load_dwordx4 v[188:191], v156, s[36:37] offset:512 nt
	global_load_dwordx4 v[192:195], v156, s[36:37] offset:576 nt
	s_waitcnt vmcnt(16)
	v_pk_fma_f32 v[198:199], v[98:99], v[142:143], v[198:199]
	v_pk_fma_f32 v[196:197], v[96:97], v[140:141], v[196:197]
	v_pk_fma_f32 v[206:207], v[94:95], v[138:139], v[206:207]
	v_pk_fma_f32 v[204:205], v[92:93], v[136:137], v[204:205]
	v_pk_fma_f32 v[210:211], v[86:87], v[134:135], v[210:211]
	v_pk_fma_f32 v[208:209], v[84:85], v[132:133], v[208:209]
	v_pk_fma_f32 v[214:215], v[74:75], v[130:131], v[214:215]
	v_pk_fma_f32 v[212:213], v[72:73], v[128:129], v[212:213]
	s_add_u32 s38, s8, 0x20000
	s_addc_u32 s39, s9, 0
	global_store_dwordx4 v156, v[196:199], s[38:39]
	global_store_dwordx4 v156, v[204:207], s[38:39] offset:64
	global_store_dwordx4 v156, v[208:211], s[38:39] offset:512
	global_store_dwordx4 v156, v[212:215], s[38:39] offset:576
	s_add_u32 s36, s0, 0x90000
	s_addc_u32 s37, s1, 0
	global_load_dwordx4 v[196:199], v156, s[36:37] nt
	global_load_dwordx4 v[204:207], v156, s[36:37] offset:64 nt
	global_load_dwordx4 v[208:211], v156, s[36:37] offset:512 nt
	global_load_dwordx4 v[212:215], v156, s[36:37] offset:576 nt
	s_waitcnt vmcnt(16)
;     __device__ __forceinline__ void operator()(const f32x4 (&acc)[2][2][4][2], const pg8::Unit& u, int wr, int wc, int fr, int fq) const {
;     ...
; #pragma unroll
;         for (int ai = 0; ai < 2; ++ai)
; #pragma unroll
;             for (int m = 0; m < 4; ++m) {
;                 const size_t off = (size_t)(row0 + ai * 128 + m * 16) * DM + col0;
; #pragma unroll
;                 for (int bj = 0; bj < 2; ++bj)
; #pragma unroll
;                     for (int n = 0; n < 2; ++n) {
;                         const f32x4 xv = *(const f32x4*)(xin + off + bj * 128 + n * 16);
;                         *(f32x4*)(out + off + bj * 128 + n * 16) = xv + gv[bj][n] * acc[ai][bj][m][n];
;                     }
;                 if (m == 3) asm volatile("" ::: "memory");
;             }
	v_pk_fma_f32 v[166:167], v[82:83], v[142:143], v[166:167]
	v_pk_fma_f32 v[164:165], v[80:81], v[140:141], v[164:165]
	v_pk_fma_f32 v[170:171], v[78:79], v[138:139], v[170:171]
	v_pk_fma_f32 v[168:169], v[76:77], v[136:137], v[168:169]
	v_pk_fma_f32 v[174:175], v[70:71], v[134:135], v[174:175]
	v_pk_fma_f32 v[172:173], v[68:69], v[132:133], v[172:173]
	v_pk_fma_f32 v[178:179], v[66:67], v[130:131], v[178:179]
	v_pk_fma_f32 v[176:177], v[64:65], v[128:129], v[176:177]
	s_add_u32 s38, s8, 0x30000
	s_addc_u32 s39, s9, 0
	global_store_dwordx4 v156, v[164:167], s[38:39]
	global_store_dwordx4 v156, v[168:171], s[38:39] offset:64
	global_store_dwordx4 v156, v[172:175], s[38:39] offset:512
	global_store_dwordx4 v156, v[176:179], s[38:39] offset:576
	s_add_u32 s36, s0, 0xa0000
	s_addc_u32 s37, s1, 0
	global_load_dwordx4 v[164:167], v156, s[36:37] nt
	global_load_dwordx4 v[168:171], v156, s[36:37] offset:64 nt
	global_load_dwordx4 v[172:175], v156, s[36:37] offset:512 nt
	global_load_dwordx4 v[176:179], v156, s[36:37] offset:576 nt
	s_waitcnt vmcnt(16)
	v_pk_fma_f32 v[182:183], v[62:63], v[142:143], v[182:183]
	v_pk_fma_f32 v[180:181], v[60:61], v[140:141], v[180:181]
	v_pk_fma_f32 v[186:187], v[58:59], v[138:139], v[186:187]
	v_pk_fma_f32 v[184:185], v[56:57], v[136:137], v[184:185]
	v_pk_fma_f32 v[190:191], v[54:55], v[134:135], v[190:191]
	v_pk_fma_f32 v[188:189], v[52:53], v[132:133], v[188:189]
	v_pk_fma_f32 v[194:195], v[42:43], v[130:131], v[194:195]
	v_pk_fma_f32 v[192:193], v[40:41], v[128:129], v[192:193]
	s_add_u32 s38, s8, 0x80000
	s_addc_u32 s39, s9, 0
	global_store_dwordx4 v156, v[180:183], s[38:39]
	global_store_dwordx4 v156, v[184:187], s[38:39] offset:64
	global_store_dwordx4 v156, v[188:191], s[38:39] offset:512
	global_store_dwordx4 v156, v[192:195], s[38:39] offset:576
	s_add_u32 s36, s0, 0xb0000
	s_addc_u32 s37, s1, 0
	global_load_dwordx4 v[180:183], v156, s[36:37] nt
	global_load_dwordx4 v[184:187], v156, s[36:37] offset:64 nt
	global_load_dwordx4 v[188:191], v156, s[36:37] offset:512 nt
	global_load_dwordx4 v[192:195], v156, s[36:37] offset:576 nt
	s_waitcnt vmcnt(16)
	v_pk_fma_f32 v[198:199], v[50:51], v[142:143], v[198:199]
	v_pk_fma_f32 v[196:197], v[48:49], v[140:141], v[196:197]
	v_pk_fma_f32 v[206:207], v[46:47], v[138:139], v[206:207]
	v_pk_fma_f32 v[204:205], v[44:45], v[136:137], v[204:205]
	v_pk_fma_f32 v[210:211], v[38:39], v[134:135], v[210:211]
	v_pk_fma_f32 v[208:209], v[36:37], v[132:133], v[208:209]
	v_pk_fma_f32 v[214:215], v[26:27], v[130:131], v[214:215]
	v_pk_fma_f32 v[212:213], v[24:25], v[128:129], v[212:213]
	s_add_u32 s38, s8, 0x90000
	s_addc_u32 s39, s9, 0
	global_store_dwordx4 v156, v[196:199], s[38:39]
	global_store_dwordx4 v156, v[204:207], s[38:39] offset:64
	global_store_dwordx4 v156, v[208:211], s[38:39] offset:512
	global_store_dwordx4 v156, v[212:215], s[38:39] offset:576
	s_waitcnt vmcnt(12)
	v_pk_fma_f32 v[166:167], v[34:35], v[142:143], v[166:167]
	v_pk_fma_f32 v[164:165], v[32:33], v[140:141], v[164:165]
	v_pk_fma_f32 v[170:171], v[30:31], v[138:139], v[170:171]
	v_pk_fma_f32 v[168:169], v[28:29], v[136:137], v[168:169]
	v_pk_fma_f32 v[174:175], v[22:23], v[134:135], v[174:175]
	v_pk_fma_f32 v[172:173], v[20:21], v[132:133], v[172:173]
	v_pk_fma_f32 v[178:179], v[10:11], v[130:131], v[178:179]
	v_pk_fma_f32 v[176:177], v[8:9], v[128:129], v[176:177]
	s_add_u32 s38, s8, 0xa0000
	s_addc_u32 s39, s9, 0
	global_store_dwordx4 v156, v[164:167], s[38:39]
	global_store_dwordx4 v156, v[168:171], s[38:39] offset:64
	global_store_dwordx4 v156, v[172:175], s[38:39] offset:512
	global_store_dwordx4 v156, v[176:179], s[38:39] offset:576
	s_waitcnt vmcnt(8)
	v_pk_fma_f32 v[182:183], v[18:19], v[142:143], v[182:183]
	v_pk_fma_f32 v[180:181], v[16:17], v[140:141], v[180:181]
	v_pk_fma_f32 v[186:187], v[14:15], v[138:139], v[186:187]
	v_pk_fma_f32 v[184:185], v[12:13], v[136:137], v[184:185]
	v_pk_fma_f32 v[190:191], v[6:7], v[134:135], v[190:191]
	v_pk_fma_f32 v[188:189], v[4:5], v[132:133], v[188:189]
	v_pk_fma_f32 v[194:195], v[2:3], v[130:131], v[194:195]
	v_pk_fma_f32 v[192:193], v[0:1], v[128:129], v[192:193]
	s_add_u32 s38, s8, 0xb0000
	s_addc_u32 s39, s9, 0
	global_store_dwordx4 v156, v[180:183], s[38:39]
	global_store_dwordx4 v156, v[184:187], s[38:39] offset:64
	global_store_dwordx4 v156, v[188:191], s[38:39] offset:512
	global_store_dwordx4 v156, v[192:195], s[38:39] offset:576
	s_cbranch_vccnz .LBB0_571
	s_andn2_b64 vcc, exec, s[6:7]
	s_cbranch_vccnz .LBB0_570
	s_barrier
	s_branch .LBB0_570

;     __device__ __forceinline__ void operator()(const f32x4 (&acc)[2][2][4][2], const pg8::Unit& u, int wr, int wc, int fr, int fq) const {
;     ...
;         for (int ai = 0; ai < 2; ++ai)
; #pragma unroll
;             for (int m = 0; m < 4; ++m) {
;                 const size_t off = (size_t)(row0 + ai * 128 + m * 16) * DM + col0;
; #pragma unroll
;                 for (int bj = 0; bj < 2; ++bj)
; #pragma unroll
;                     for (int n = 0; n < 2; ++n) {
;                         const f32x4 xv = *(const f32x4*)(xin + off + bj * 128 + n * 16);
;                         *(f32x4*)(out + off + bj * 128 + n * 16) = xv + gv[bj][n] * acc[ai][bj][m][n];
;                     }
;                 if (m == 3) asm volatile("" ::: "memory");
;             }
.LBB0_1107:
	s_ashr_i32 s21, s28, 3
	v_lshl_or_b32 v128, s58, 8, v160
	s_mul_hi_i32 s23, s21, 0x3000
	s_mulk_i32 s21, 0x3000
	v_lshl_add_u32 v216, s28, 8, v158
	s_add_u32 s30, s47, s21
	v_ashrrev_i32_e32 v129, 31, v128
	v_ashrrev_i32_e32 v217, 31, v216
	v_or_b32_e32 v180, 16, v216
	v_or_b32_e32 v196, 32, v216
	s_addc_u32 s31, s48, s23
	v_lshlrev_b64 v[200:201], 2, v[128:129]
	v_lshlrev_b64 v[138:139], 12, v[216:217]
	v_ashrrev_i32_e32 v181, 31, v180
	v_ashrrev_i32_e32 v197, 31, v196
	v_or_b32_e32 v216, 48, v216
	v_lshl_add_u64 v[136:137], s[30:31], 0, v[200:201]
	v_lshl_add_u64 v[138:139], s[4:5], 0, v[138:139]
	v_lshlrev_b64 v[180:181], 12, v[180:181]
	v_lshlrev_b64 v[196:197], 12, v[196:197]
	v_ashrrev_i32_e32 v217, 31, v216
	global_load_dwordx4 v[132:135], v[136:137], off
	global_load_dwordx4 v[128:131], v[136:137], off offset:64
	v_lshl_add_u64 v[156:157], v[138:139], 0, v[200:201]
	v_lshl_add_u64 v[180:181], s[4:5], 0, v[180:181]
	v_lshl_add_u64 v[196:197], s[4:5], 0, v[196:197]
	v_lshlrev_b64 v[216:217], 12, v[216:217]
	global_load_dwordx4 v[164:167], v[156:157], off nt
	global_load_dwordx4 v[140:143], v[136:137], off offset:512
	s_nop 0
	global_load_dwordx4 v[136:139], v[136:137], off offset:576
	s_nop 0
	global_load_dwordx4 v[168:171], v[156:157], off offset:64 nt
	global_load_dwordx4 v[172:175], v[156:157], off offset:512 nt
	global_load_dwordx4 v[176:179], v[156:157], off offset:576 nt
	v_lshl_add_u64 v[232:233], v[180:181], 0, v[200:201]
	v_lshl_add_u64 v[234:235], v[196:197], 0, v[200:201]
	v_lshl_add_u64 v[216:217], s[4:5], 0, v[216:217]
	global_load_dwordx4 v[180:183], v[232:233], off nt
	global_load_dwordx4 v[184:187], v[232:233], off offset:64 nt
	global_load_dwordx4 v[188:191], v[232:233], off offset:512 nt
	global_load_dwordx4 v[192:195], v[232:233], off offset:576 nt
	global_load_dwordx4 v[196:199], v[234:235], off nt
	global_load_dwordx4 v[204:207], v[234:235], off offset:64 nt
	global_load_dwordx4 v[208:211], v[234:235], off offset:512 nt
	global_load_dwordx4 v[212:215], v[234:235], off offset:576 nt
	v_lshl_add_u64 v[200:201], v[216:217], 0, v[200:201]
	global_load_dwordx4 v[216:219], v[200:201], off nt
	global_load_dwordx4 v[220:223], v[200:201], off offset:64 nt
	global_load_dwordx4 v[224:227], v[200:201], off offset:512 nt
	global_load_dwordx4 v[228:231], v[200:201], off offset:576 nt
	s_waitcnt vmcnt(0)
	v_pk_fma_f32 v[126:127], v[126:127], v[134:135], v[166:167]
	v_add_co_u32_e32 v166, vcc, s54, v156
	v_pk_fma_f32 v[124:125], v[124:125], v[132:133], v[164:165]
	s_nop 0
	v_addc_co_u32_e32 v167, vcc, 0, v157, vcc
	v_pk_fma_f32 v[122:123], v[122:123], v[130:131], v[170:171]
	v_pk_fma_f32 v[98:99], v[98:99], v[138:139], v[178:179]
	v_pk_fma_f32 v[96:97], v[96:97], v[136:137], v[176:177]
	v_add_co_u32_e32 v170, vcc, s55, v156
	v_pk_fma_f32 v[120:121], v[120:121], v[128:129], v[168:169]
	v_pk_fma_f32 v[106:107], v[106:107], v[142:143], v[174:175]
	v_pk_fma_f32 v[104:105], v[104:105], v[140:141], v[172:173]
	global_store_dwordx4 v[156:157], v[124:127], off
	global_store_dwordx4 v[156:157], v[120:123], off offset:64
	global_store_dwordx4 v[156:157], v[104:107], off offset:512
	global_store_dwordx4 v[156:157], v[96:99], off offset:576
	v_pk_fma_f32 v[74:75], v[74:75], v[138:139], v[214:215]
	v_pk_fma_f32 v[72:73], v[72:73], v[136:137], v[212:213]
	v_pk_fma_f32 v[98:99], v[118:119], v[134:135], v[182:183]
	v_pk_fma_f32 v[96:97], v[116:117], v[132:133], v[180:181]
	v_addc_co_u32_e32 v171, vcc, 0, v157, vcc
	v_pk_fma_f32 v[106:107], v[114:115], v[130:131], v[186:187]
	v_pk_fma_f32 v[104:105], v[112:113], v[128:129], v[184:185]
	v_pk_fma_f32 v[90:91], v[90:91], v[142:143], v[190:191]
	v_pk_fma_f32 v[88:89], v[88:89], v[140:141], v[188:189]
	v_pk_fma_f32 v[86:87], v[86:87], v[138:139], v[194:195]
	v_pk_fma_f32 v[84:85], v[84:85], v[136:137], v[192:193]
	v_pk_fma_f32 v[110:111], v[110:111], v[134:135], v[198:199]
	v_pk_fma_f32 v[108:109], v[108:109], v[132:133], v[196:197]
	v_pk_fma_f32 v[102:103], v[102:103], v[130:131], v[206:207]
	v_pk_fma_f32 v[100:101], v[100:101], v[128:129], v[204:205]
	v_pk_fma_f32 v[78:79], v[78:79], v[142:143], v[210:211]
	v_pk_fma_f32 v[76:77], v[76:77], v[140:141], v[208:209]
	v_pk_fma_f32 v[94:95], v[94:95], v[134:135], v[218:219]
	v_pk_fma_f32 v[92:93], v[92:93], v[132:133], v[216:217]
	global_store_dwordx4 v[232:233], v[96:99], off
	global_store_dwordx4 v[232:233], v[104:107], off offset:64
	global_store_dwordx4 v[232:233], v[88:91], off offset:512
	global_store_dwordx4 v[232:233], v[84:87], off offset:576
	global_store_dwordx4 v[234:235], v[108:111], off
	global_store_dwordx4 v[234:235], v[100:103], off offset:64
	global_store_dwordx4 v[234:235], v[76:79], off offset:512
	global_store_dwordx4 v[234:235], v[72:75], off offset:576
	global_store_dwordx4 v[200:201], v[92:95], off
	v_pk_fma_f32 v[70:71], v[70:71], v[142:143], v[226:227]
	v_pk_fma_f32 v[74:75], v[82:83], v[130:131], v[222:223]
	v_pk_fma_f32 v[72:73], v[80:81], v[128:129], v[220:221]
	v_pk_fma_f32 v[68:69], v[68:69], v[140:141], v[224:225]
	v_pk_fma_f32 v[66:67], v[66:67], v[138:139], v[230:231]
	v_pk_fma_f32 v[64:65], v[64:65], v[136:137], v[228:229]
	v_add_co_u32_e32 v174, vcc, s56, v156
	global_store_dwordx4 v[200:201], v[72:75], off offset:64
	global_store_dwordx4 v[200:201], v[68:71], off offset:512
	global_store_dwordx4 v[200:201], v[64:67], off offset:576
	v_addc_co_u32_e32 v175, vcc, 0, v157, vcc
	v_lshl_add_u64 v[164:165], v[156:157], 0, s[12:13]
	v_add_co_u32_e32 v176, vcc, s57, v156
	global_load_dwordx4 v[64:67], v[164:165], off offset:64 nt
	global_load_dwordx4 v[68:71], v[164:165], off offset:512 nt
	global_load_dwordx4 v[72:75], v[166:167], off nt
	global_load_dwordx4 v[76:79], v[164:165], off offset:576 nt
	v_lshl_add_u64 v[168:169], v[156:157], 0, s[14:15]
	global_load_dwordx4 v[80:83], v[170:171], off nt
	global_load_dwordx4 v[84:87], v[168:169], off offset:64 nt
	global_load_dwordx4 v[88:91], v[168:169], off offset:512 nt
	global_load_dwordx4 v[92:95], v[168:169], off offset:576 nt
	v_lshl_add_u64 v[172:173], v[156:157], 0, s[16:17]
	global_load_dwordx4 v[96:99], v[174:175], off nt
	global_load_dwordx4 v[100:103], v[172:173], off offset:64 nt
	global_load_dwordx4 v[104:107], v[172:173], off offset:512 nt
	global_load_dwordx4 v[108:111], v[172:173], off offset:576 nt
	v_addc_co_u32_e32 v177, vcc, 0, v157, vcc
	v_lshl_add_u64 v[156:157], v[156:157], 0, s[18:19]
	global_load_dwordx4 v[112:115], v[176:177], off nt
	global_load_dwordx4 v[116:119], v[156:157], off offset:64 nt
	global_load_dwordx4 v[120:123], v[156:157], off offset:512 nt
	global_load_dwordx4 v[124:127], v[156:157], off offset:576 nt
	s_andn2_b64 vcc, exec, s[0:1]
	s_mov_b64 s[0:1], -1
	s_waitcnt vmcnt(15)
;     __device__ __forceinline__ void operator()(const f32x4 (&acc)[2][2][4][2], const pg8::Unit& u, int wr, int wc, int fr, int fq) const {
;     ...
;                 for (int bj = 0; bj < 2; ++bj)
; #pragma unroll
;                     for (int n = 0; n < 2; ++n) {
;                         const f32x4 xv = *(const f32x4*)(xin + off + bj * 128 + n * 16);
;                         *(f32x4*)(out + off + bj * 128 + n * 16) = xv + gv[bj][n] * acc[ai][bj][m][n];
;                     }
;                 if (m == 3) asm volatile("" ::: "memory");
	v_pk_fma_f32 v[58:59], v[58:59], v[130:131], v[66:67]
	v_pk_fma_f32 v[56:57], v[56:57], v[128:129], v[64:65]
	s_waitcnt vmcnt(13)
	v_pk_fma_f32 v[62:63], v[62:63], v[134:135], v[74:75]
	v_pk_fma_f32 v[60:61], v[60:61], v[132:133], v[72:73]
	v_pk_fma_f32 v[42:43], v[42:43], v[142:143], v[70:71]
	v_pk_fma_f32 v[40:41], v[40:41], v[140:141], v[68:69]
	s_waitcnt vmcnt(12)
	v_pk_fma_f32 v[34:35], v[34:35], v[138:139], v[78:79]
	s_waitcnt vmcnt(4)
	v_pk_fma_f32 v[10:11], v[10:11], v[138:139], v[110:111]
	v_pk_fma_f32 v[8:9], v[8:9], v[136:137], v[108:109]
	v_pk_fma_f32 v[32:33], v[32:33], v[136:137], v[76:77]
	v_pk_fma_f32 v[54:55], v[54:55], v[134:135], v[82:83]
	v_pk_fma_f32 v[52:53], v[52:53], v[132:133], v[80:81]
	v_pk_fma_f32 v[50:51], v[50:51], v[130:131], v[86:87]
	v_pk_fma_f32 v[48:49], v[48:49], v[128:129], v[84:85]
	v_pk_fma_f32 v[30:31], v[30:31], v[142:143], v[90:91]
	v_pk_fma_f32 v[28:29], v[28:29], v[140:141], v[88:89]
	v_pk_fma_f32 v[26:27], v[26:27], v[138:139], v[94:95]
	v_pk_fma_f32 v[24:25], v[24:25], v[136:137], v[92:93]
	v_pk_fma_f32 v[46:47], v[46:47], v[134:135], v[98:99]
	v_pk_fma_f32 v[44:45], v[44:45], v[132:133], v[96:97]
	v_pk_fma_f32 v[38:39], v[38:39], v[130:131], v[102:103]
	v_pk_fma_f32 v[36:37], v[36:37], v[128:129], v[100:101]
	v_pk_fma_f32 v[14:15], v[14:15], v[142:143], v[106:107]
	v_pk_fma_f32 v[12:13], v[12:13], v[140:141], v[104:105]
	s_waitcnt vmcnt(3)
	v_pk_fma_f32 v[22:23], v[22:23], v[134:135], v[114:115]
	global_store_dwordx4 v[166:167], v[60:63], off
	global_store_dwordx4 v[164:165], v[56:59], off offset:64
	global_store_dwordx4 v[164:165], v[40:43], off offset:512
	global_store_dwordx4 v[164:165], v[32:35], off offset:576
	global_store_dwordx4 v[170:171], v[52:55], off
	global_store_dwordx4 v[168:169], v[48:51], off offset:64
	global_store_dwordx4 v[168:169], v[28:31], off offset:512
	global_store_dwordx4 v[168:169], v[24:27], off offset:576
	global_store_dwordx4 v[174:175], v[44:47], off
	global_store_dwordx4 v[172:173], v[36:39], off offset:64
	global_store_dwordx4 v[172:173], v[12:15], off offset:512
	global_store_dwordx4 v[172:173], v[8:11], off offset:576
	v_pk_fma_f32 v[20:21], v[20:21], v[132:133], v[112:113]
	s_waitcnt vmcnt(13)
	v_pk_fma_f32 v[6:7], v[6:7], v[142:143], v[122:123]
	v_pk_fma_f32 v[10:11], v[18:19], v[130:131], v[118:119]
	v_pk_fma_f32 v[8:9], v[16:17], v[128:129], v[116:117]
	v_pk_fma_f32 v[4:5], v[4:5], v[140:141], v[120:121]
	s_waitcnt vmcnt(12)
	v_pk_fma_f32 v[2:3], v[2:3], v[138:139], v[126:127]
	v_pk_fma_f32 v[0:1], v[0:1], v[136:137], v[124:125]
	global_store_dwordx4 v[176:177], v[20:23], off
	global_store_dwordx4 v[156:157], v[8:11], off offset:64
	global_store_dwordx4 v[156:157], v[4:7], off offset:512
	global_store_dwordx4 v[156:157], v[0:3], off offset:576
	s_cbranch_vccnz .LBB0_1096
	s_andn2_b64 vcc, exec, s[8:9]
	s_cbranch_vccnz .LBB0_1095
	s_barrier
	s_branch .LBB0_1095
